# grid barrier: arrival counter sharded 8 ways by blockIdx&7 (256 B apart), 8 lanes poll all shards; phase 0 zeroes the 8 shard words
# speedup vs baseline: 1.0131x; 1.0131x over previous
; DI int tid_l() { int t = threadIdx.x; asm volatile("" : "+v"(t)); return t; }
; DI void phase0(const Params& p, char* lds) {
;     ...
;   if (blockIdx.x == 0) { const int t_ = tid_l(); if (t_ < 128) ((unsigned*)(ws + OFF_CNT))[t_] = 0u; if (t_ == 128) ((unsigned*)(ws + OFF_CNT))[256] = 0u; }
.LBB0_44:
	s_or_b64 exec, exec, s[4:5]
	v_subrev_u32_e32 v3, s3, v2
	v_cmp_gt_u32_e32 vcc, 8, v3
	s_and_saveexec_b64 s[4:5], vcc
	s_cbranch_execz .LBB0_46
	v_lshlrev_b32_e32 v1, 8, v3
	v_add_u32_e32 v1, 0x1ee14000, v1
	v_mov_b32_e32 v2, 0
	global_store_dword v1, v2, s[10:11] offset:1024

; #define GAS __attribute__((address_space(1)))
; DI void grid_barrier(unsigned* ctr, const unsigned target) {
;   asm volatile("s_waitcnt vmcnt(0)" ::: "memory");
;   __syncthreads();
;   if (threadIdx.x == 0) {
;     __builtin_amdgcn_fence(__ATOMIC_RELEASE, "agent");
;     asm volatile("s_waitcnt vmcnt(0)" ::: "memory");
;     __hip_atomic_fetch_add((GAS unsigned*)ctr, 1u, __ATOMIC_RELAXED, __HIP_MEMORY_SCOPE_AGENT);
;     while (__hip_atomic_load((GAS unsigned*)ctr, __ATOMIC_RELAXED, __HIP_MEMORY_SCOPE_AGENT) < target) __builtin_amdgcn_s_sleep(1);
;     __builtin_amdgcn_fence(__ATOMIC_ACQUIRE, "agent");
;     asm volatile("s_waitcnt vmcnt(0)" ::: "memory");
;   }
;   __syncthreads();
; }
.LBB0_135:
	v_readlane_b32 s3, v254, 12
	s_add_i32 s2, s3, 1
	s_cmp_ge_i32 s2, s79
	s_cbranch_scc1 .LBB0_156
	s_cmp_lg_u32 s3, s78
	s_mov_b64 s[4:5], -1
	s_cbranch_scc0 .LBB0_144
	s_waitcnt vmcnt(0)
	s_waitcnt vmcnt(63) expcnt(7) lgkmcnt(15)
	s_barrier
	s_mov_b64 s[4:5], exec
	v_readlane_b32 s6, v254, 26
	v_readlane_b32 s7, v254, 27
	s_and_b64 s[6:7], s[4:5], s[6:7]
	s_mov_b64 exec, s[6:7]
	s_cbranch_execz .LBB0_143
	s_mov_b64 s[10:11], exec
	buffer_wbl2 sc1
	s_waitcnt vmcnt(0)
	s_waitcnt vmcnt(0)
	v_mbcnt_lo_u32_b32 v0, s10, 0
	s_add_u32 s8, s14, 0x1ee14400
	v_mbcnt_hi_u32_b32 v0, s11, v0
	s_addc_u32 s9, s15, 0
	v_cmp_eq_u32_e32 vcc, 0, v0
	s_and_saveexec_b64 s[12:13], vcc
	s_cbranch_execz .LBB0_140
	s_bcnt1_i32_b64 s3, s[10:11]
	v_mov_b32_e32 v0, s3
	v_readlane_b32 s100, v254, 0
	s_and_b32 s100, s100, 7
	s_lshl_b32 s100, s100, 8
	s_add_u32 s100, s8, s100
	s_addc_u32 s101, s9, 0
	global_atomic_add v1, v0, s[100:101]
.LBB0_140:
	s_or_b64 exec, exec, s[12:13]
	s_mov_b64 exec, 0xff
	v_mbcnt_lo_u32_b32 v3, -1, 0
	v_lshlrev_b32_e32 v3, 8, v3
	global_load_dword v0, v3, s[8:9] sc1
	s_load_dword s6, s[80:81], 0x0
	v_readlane_b32 s3, v254, 12
	s_sub_i32 s3, s3, s78
	s_waitcnt lgkmcnt(0)
	s_mul_i32 s3, s6, s3
	s_waitcnt vmcnt(0)
	s_lshr_b32 s3, s3, 3
	v_cmp_gt_u32_e32 vcc, s3, v0
	s_cbranch_vccz .LBB0_142
.LBB0_141:
	s_sleep 1
	global_load_dword v0, v3, s[8:9] sc1
	s_waitcnt vmcnt(0)
	v_cmp_gt_u32_e32 vcc, s3, v0
	s_cbranch_vccnz .LBB0_141

; #define GAS __attribute__((address_space(1)))
; DI void grid_barrier(unsigned* ctr, const unsigned target) {
;   asm volatile("s_waitcnt vmcnt(0)" ::: "memory");
;   __syncthreads();
;   if (threadIdx.x == 0) {
;     __builtin_amdgcn_fence(__ATOMIC_RELEASE, "agent");
;     asm volatile("s_waitcnt vmcnt(0)" ::: "memory");
;     __hip_atomic_fetch_add((GAS unsigned*)ctr, 1u, __ATOMIC_RELAXED, __HIP_MEMORY_SCOPE_AGENT);
;     while (__hip_atomic_load((GAS unsigned*)ctr, __ATOMIC_RELAXED, __HIP_MEMORY_SCOPE_AGENT) < target) __builtin_amdgcn_s_sleep(1);
;     __builtin_amdgcn_fence(__ATOMIC_ACQUIRE, "agent");
;     asm volatile("s_waitcnt vmcnt(0)" ::: "memory");
;   }
;   __syncthreads();
; }
.LBB0_168:
	v_readlane_b32 s3, v254, 12
	s_add_i32 s14, s3, 2
	s_cmp_ge_i32 s14, s79
	s_cbranch_scc1 .LBB0_189
	s_cmp_lg_u32 s2, s78
	s_mov_b64 s[4:5], -1
	s_cbranch_scc0 .LBB0_177
	s_waitcnt vmcnt(0)
	s_waitcnt vmcnt(63) expcnt(7) lgkmcnt(15)
	s_barrier
	s_mov_b64 s[4:5], exec
	v_readlane_b32 s6, v254, 26
	v_readlane_b32 s7, v254, 27
	s_and_b64 s[6:7], s[4:5], s[6:7]
	s_mov_b64 exec, s[6:7]
	s_cbranch_execz .LBB0_176
	s_mov_b64 s[10:11], exec
	buffer_wbl2 sc1
	s_waitcnt vmcnt(0)
	s_waitcnt vmcnt(0)
	v_mbcnt_lo_u32_b32 v0, s10, 0
	s_add_u32 s8, s26, 0x1ee14400
	v_mbcnt_hi_u32_b32 v0, s11, v0
	s_addc_u32 s9, s27, 0
	v_cmp_eq_u32_e32 vcc, 0, v0
	s_and_saveexec_b64 s[12:13], vcc
	s_cbranch_execz .LBB0_173
	s_bcnt1_i32_b64 s3, s[10:11]
	v_mov_b32_e32 v0, s3
	v_readlane_b32 s100, v254, 0
	s_and_b32 s100, s100, 7
	s_lshl_b32 s100, s100, 8
	s_add_u32 s100, s8, s100
	s_addc_u32 s101, s9, 0
	global_atomic_add v1, v0, s[100:101]
.LBB0_173:
	s_or_b64 exec, exec, s[12:13]
	s_mov_b64 exec, 0xff
	v_mbcnt_lo_u32_b32 v3, -1, 0
	v_lshlrev_b32_e32 v3, 8, v3
	global_load_dword v0, v3, s[8:9] sc1
	s_load_dword s3, s[80:81], 0x0
	s_sub_i32 s2, s2, s78
	s_waitcnt lgkmcnt(0)
	s_mul_i32 s2, s3, s2
	s_waitcnt vmcnt(0)
	s_lshr_b32 s2, s2, 3
	v_cmp_gt_u32_e32 vcc, s2, v0
	s_cbranch_vccz .LBB0_175
.LBB0_174:
	s_sleep 1
	global_load_dword v0, v3, s[8:9] sc1
	s_waitcnt vmcnt(0)
	v_cmp_gt_u32_e32 vcc, s2, v0
	s_cbranch_vccnz .LBB0_174

; #define GAS __attribute__((address_space(1)))
; DI void grid_barrier(unsigned* ctr, const unsigned target) {
;   asm volatile("s_waitcnt vmcnt(0)" ::: "memory");
;   __syncthreads();
;   if (threadIdx.x == 0) {
;     __builtin_amdgcn_fence(__ATOMIC_RELEASE, "agent");
;     asm volatile("s_waitcnt vmcnt(0)" ::: "memory");
;     __hip_atomic_fetch_add((GAS unsigned*)ctr, 1u, __ATOMIC_RELAXED, __HIP_MEMORY_SCOPE_AGENT);
;     while (__hip_atomic_load((GAS unsigned*)ctr, __ATOMIC_RELAXED, __HIP_MEMORY_SCOPE_AGENT) < target) __builtin_amdgcn_s_sleep(1);
;     __builtin_amdgcn_fence(__ATOMIC_ACQUIRE, "agent");
;     asm volatile("s_waitcnt vmcnt(0)" ::: "memory");
;   }
;   __syncthreads();
; }
.LBB0_241:
	v_readlane_b32 s2, v254, 12
	v_readlane_b32 s78, v254, 32
	s_add_i32 s28, s2, 3
	v_readlane_b32 s79, v254, 33
	s_cmp_ge_i32 s28, s79
	s_cbranch_scc1 .LBB0_262
	v_readlane_b32 s6, v254, 50
	v_readlane_b32 s80, v254, 34
	s_cmp_lg_u32 s6, s78
	s_mov_b64 s[4:5], -1
	v_readlane_b32 s81, v254, 35
	s_cbranch_scc0 .LBB0_250
	s_waitcnt vmcnt(0)
	s_barrier
	s_mov_b64 s[4:5], exec
	v_readlane_b32 s2, v254, 26
	v_readlane_b32 s3, v254, 27
	s_and_b64 s[2:3], s[4:5], s[2:3]
	s_mov_b64 exec, s[2:3]
	s_cbranch_execz .LBB0_249
	s_mov_b64 s[10:11], exec
	v_readlane_b32 s2, v254, 48
	buffer_wbl2 sc1
	s_waitcnt vmcnt(0)
	s_waitcnt vmcnt(0)
	v_mbcnt_lo_u32_b32 v0, s10, 0
	v_readlane_b32 s3, v254, 49
	s_add_u32 s8, s2, 0x1ee14400
	v_mbcnt_hi_u32_b32 v0, s11, v0
	s_addc_u32 s9, s3, 0
	v_cmp_eq_u32_e32 vcc, 0, v0
	s_and_saveexec_b64 s[12:13], vcc
	s_cbranch_execz .LBB0_246
	s_bcnt1_i32_b64 s2, s[10:11]
	v_mov_b32_e32 v0, s2
	v_readlane_b32 s100, v254, 0
	s_and_b32 s100, s100, 7
	s_lshl_b32 s100, s100, 8
	s_add_u32 s100, s8, s100
	s_addc_u32 s101, s9, 0
	global_atomic_add v1, v0, s[100:101]
.LBB0_246:
	s_or_b64 exec, exec, s[12:13]
	s_mov_b64 exec, 0xff
	v_mbcnt_lo_u32_b32 v3, -1, 0
	v_lshlrev_b32_e32 v3, 8, v3
	global_load_dword v0, v3, s[8:9] sc1
	s_load_dword s3, s[80:81], 0x0
	s_sub_i32 s2, s6, s78
	s_waitcnt lgkmcnt(0)
	s_mul_i32 s2, s3, s2
	s_waitcnt vmcnt(0)
	s_lshr_b32 s2, s2, 3
	v_cmp_gt_u32_e32 vcc, s2, v0
	s_cbranch_vccz .LBB0_248

; #define GAS __attribute__((address_space(1)))
; DI void grid_barrier(unsigned* ctr, const unsigned target) {
;   asm volatile("s_waitcnt vmcnt(0)" ::: "memory");
;   __syncthreads();
;   if (threadIdx.x == 0) {
;     __builtin_amdgcn_fence(__ATOMIC_RELEASE, "agent");
;     asm volatile("s_waitcnt vmcnt(0)" ::: "memory");
;     __hip_atomic_fetch_add((GAS unsigned*)ctr, 1u, __ATOMIC_RELAXED, __HIP_MEMORY_SCOPE_AGENT);
;     while (__hip_atomic_load((GAS unsigned*)ctr, __ATOMIC_RELAXED, __HIP_MEMORY_SCOPE_AGENT) < target) __builtin_amdgcn_s_sleep(1);
;     __builtin_amdgcn_fence(__ATOMIC_ACQUIRE, "agent");
;     asm volatile("s_waitcnt vmcnt(0)" ::: "memory");
;   }
;   __syncthreads();
; }
.LBB0_279:
	v_readlane_b32 s2, v254, 12
	s_add_i32 s24, s2, 4
	s_cmp_ge_i32 s24, s79
	s_cbranch_scc1 .LBB0_300
	s_cmp_lg_u32 s28, s78
	s_mov_b64 s[4:5], -1
	s_cbranch_scc0 .LBB0_288
	s_waitcnt vmcnt(0)
	s_barrier
	s_mov_b64 s[4:5], exec
	v_readlane_b32 s2, v254, 26
	v_readlane_b32 s3, v254, 27
	s_and_b64 s[2:3], s[4:5], s[2:3]
	s_mov_b64 exec, s[2:3]
	s_cbranch_execz .LBB0_287
	s_add_u32 s8, s10, 0x1ee14400
	s_addc_u32 s9, s11, 0
	s_mov_b64 s[10:11], exec
	buffer_wbl2 sc1
	s_waitcnt vmcnt(0)
	s_waitcnt vmcnt(0)
	v_mbcnt_lo_u32_b32 v0, s10, 0
	v_mbcnt_hi_u32_b32 v0, s11, v0
	v_cmp_eq_u32_e32 vcc, 0, v0
	s_and_saveexec_b64 s[12:13], vcc
	s_cbranch_execz .LBB0_284
	s_bcnt1_i32_b64 s2, s[10:11]
	v_mov_b32_e32 v0, s2
	v_readlane_b32 s100, v254, 0
	s_and_b32 s100, s100, 7
	s_lshl_b32 s100, s100, 8
	s_add_u32 s100, s8, s100
	s_addc_u32 s101, s9, 0
	global_atomic_add v1, v0, s[100:101]
.LBB0_284:
	s_or_b64 exec, exec, s[12:13]
	s_mov_b64 exec, 0xff
	v_mbcnt_lo_u32_b32 v3, -1, 0
	v_lshlrev_b32_e32 v3, 8, v3
	global_load_dword v0, v3, s[8:9] sc1
	s_load_dword s3, s[80:81], 0x0
	s_sub_i32 s2, s28, s78
	s_waitcnt lgkmcnt(0)
	s_mul_i32 s2, s3, s2
	s_waitcnt vmcnt(0)
	s_lshr_b32 s2, s2, 3
	v_cmp_gt_u32_e32 vcc, s2, v0
	s_cbranch_vccz .LBB0_286

; #define GAS __attribute__((address_space(1)))
; DI void grid_barrier(unsigned* ctr, const unsigned target) {
;   asm volatile("s_waitcnt vmcnt(0)" ::: "memory");
;   __syncthreads();
;   if (threadIdx.x == 0) {
;     __builtin_amdgcn_fence(__ATOMIC_RELEASE, "agent");
;     asm volatile("s_waitcnt vmcnt(0)" ::: "memory");
;     __hip_atomic_fetch_add((GAS unsigned*)ctr, 1u, __ATOMIC_RELAXED, __HIP_MEMORY_SCOPE_AGENT);
;     while (__hip_atomic_load((GAS unsigned*)ctr, __ATOMIC_RELAXED, __HIP_MEMORY_SCOPE_AGENT) < target) __builtin_amdgcn_s_sleep(1);
;     __builtin_amdgcn_fence(__ATOMIC_ACQUIRE, "agent");
;     asm volatile("s_waitcnt vmcnt(0)" ::: "memory");
;   }
;   __syncthreads();
; }
.LBB0_504:
	v_readlane_b32 s2, v254, 12
	s_add_i32 s3, s2, 1
	s_cmp_ge_i32 s3, s79
	s_cbranch_scc1 .LBB0_525
	s_cmp_lg_u32 s2, s78
	s_mov_b64 s[4:5], -1
	s_cbranch_scc0 .LBB0_513
	s_waitcnt vmcnt(0)
	s_waitcnt vmcnt(63) expcnt(7) lgkmcnt(15)
	s_barrier
	s_mov_b64 s[4:5], exec
	v_readlane_b32 s6, v254, 26
	v_readlane_b32 s7, v254, 27
	s_and_b64 s[6:7], s[4:5], s[6:7]
	s_mov_b64 exec, s[6:7]
	s_cbranch_execz .LBB0_512
	s_load_dword s2, s[80:81], 0x0
	s_mov_b64 s[8:9], exec
	buffer_wbl2 sc1
	s_waitcnt vmcnt(0) lgkmcnt(0)
	s_waitcnt vmcnt(0)
	v_mbcnt_lo_u32_b32 v0, s8, 0
	s_add_u32 s6, s18, 0x1ee14400
	v_mbcnt_hi_u32_b32 v0, s9, v0
	s_addc_u32 s7, s19, 0
	v_cmp_eq_u32_e32 vcc, 0, v0
	s_and_saveexec_b64 s[10:11], vcc
	s_cbranch_execz .LBB0_509
	s_bcnt1_i32_b64 s8, s[8:9]
	v_mov_b32_e32 v0, s8
	v_readlane_b32 s100, v254, 0
	s_and_b32 s100, s100, 7
	s_lshl_b32 s100, s100, 8
	s_add_u32 s100, s6, s100
	s_addc_u32 s101, s7, 0
	global_atomic_add v1, v0, s[100:101]
.LBB0_509:
	s_or_b64 exec, exec, s[10:11]
	s_mov_b64 exec, 0xff
	v_mbcnt_lo_u32_b32 v3, -1, 0
	v_lshlrev_b32_e32 v3, 8, v3
	global_load_dword v0, v3, s[6:7] sc1
	v_readlane_b32 s8, v254, 12
	s_sub_i32 s8, s8, s78
	s_mul_i32 s2, s2, s8
	s_waitcnt vmcnt(0)
	s_lshr_b32 s2, s2, 3
	v_cmp_gt_u32_e32 vcc, s2, v0
	s_cbranch_vccz .LBB0_511
.LBB0_510:
	s_sleep 1
	global_load_dword v0, v3, s[6:7] sc1
	s_waitcnt vmcnt(0)
	v_cmp_gt_u32_e32 vcc, s2, v0
	s_cbranch_vccnz .LBB0_510

; #define GAS __attribute__((address_space(1)))
; DI void grid_barrier(unsigned* ctr, const unsigned target) {
;   asm volatile("s_waitcnt vmcnt(0)" ::: "memory");
;   __syncthreads();
;   if (threadIdx.x == 0) {
;     __builtin_amdgcn_fence(__ATOMIC_RELEASE, "agent");
;     asm volatile("s_waitcnt vmcnt(0)" ::: "memory");
;     __hip_atomic_fetch_add((GAS unsigned*)ctr, 1u, __ATOMIC_RELAXED, __HIP_MEMORY_SCOPE_AGENT);
;     while (__hip_atomic_load((GAS unsigned*)ctr, __ATOMIC_RELAXED, __HIP_MEMORY_SCOPE_AGENT) < target) __builtin_amdgcn_s_sleep(1);
;     __builtin_amdgcn_fence(__ATOMIC_ACQUIRE, "agent");
;     asm volatile("s_waitcnt vmcnt(0)" ::: "memory");
;   }
;   __syncthreads();
; }
.LBB0_537:
	v_readlane_b32 s2, v254, 12
	s_add_i32 s2, s2, 2
	s_cmp_ge_i32 s2, s79
	s_cbranch_scc1 .LBB0_558
	s_cmp_lg_u32 s3, s78
	s_mov_b64 s[8:9], -1
	s_cbranch_scc0 .LBB0_546
	s_waitcnt vmcnt(0)
	s_waitcnt vmcnt(63) expcnt(7) lgkmcnt(15)
	s_barrier
	s_mov_b64 s[8:9], exec
	v_readlane_b32 s10, v254, 26
	v_readlane_b32 s11, v254, 27
	s_and_b64 s[10:11], s[8:9], s[10:11]
	s_mov_b64 exec, s[10:11]
	s_cbranch_execz .LBB0_545
	s_mov_b64 s[10:11], exec
	buffer_wbl2 sc1
	s_waitcnt vmcnt(0)
	s_waitcnt vmcnt(0)
	v_mbcnt_lo_u32_b32 v0, s10, 0
	s_add_u32 s4, s4, 0x1ee14400
	v_mbcnt_hi_u32_b32 v0, s11, v0
	s_addc_u32 s5, s5, 0
	v_cmp_eq_u32_e32 vcc, 0, v0
	s_and_saveexec_b64 s[12:13], vcc
	s_cbranch_execz .LBB0_542
	s_bcnt1_i32_b64 s10, s[10:11]
	v_mov_b32_e32 v0, s10
	v_readlane_b32 s100, v254, 0
	s_and_b32 s100, s100, 7
	s_lshl_b32 s100, s100, 8
	s_add_u32 s100, s4, s100
	s_addc_u32 s101, s5, 0
	global_atomic_add v1, v0, s[100:101]
.LBB0_542:
	s_or_b64 exec, exec, s[12:13]
	s_mov_b64 exec, 0xff
	v_mbcnt_lo_u32_b32 v3, -1, 0
	v_lshlrev_b32_e32 v3, 8, v3
	global_load_dword v0, v3, s[4:5] sc1
	s_load_dword s10, s[80:81], 0x0
	s_sub_i32 s3, s3, s78
	s_waitcnt lgkmcnt(0)
	s_mul_i32 s3, s10, s3
	s_waitcnt vmcnt(0)
	s_lshr_b32 s3, s3, 3
	v_cmp_gt_u32_e32 vcc, s3, v0
	s_cbranch_vccz .LBB0_544
.LBB0_543:
	s_sleep 1
	global_load_dword v0, v3, s[4:5] sc1
	s_waitcnt vmcnt(0)
	v_cmp_gt_u32_e32 vcc, s3, v0
	s_cbranch_vccnz .LBB0_543

; #define GAS __attribute__((address_space(1)))
; DI void grid_barrier(unsigned* ctr, const unsigned target) {
;   asm volatile("s_waitcnt vmcnt(0)" ::: "memory");
;   __syncthreads();
;   if (threadIdx.x == 0) {
;     __builtin_amdgcn_fence(__ATOMIC_RELEASE, "agent");
;     asm volatile("s_waitcnt vmcnt(0)" ::: "memory");
;     __hip_atomic_fetch_add((GAS unsigned*)ctr, 1u, __ATOMIC_RELAXED, __HIP_MEMORY_SCOPE_AGENT);
;     while (__hip_atomic_load((GAS unsigned*)ctr, __ATOMIC_RELAXED, __HIP_MEMORY_SCOPE_AGENT) < target) __builtin_amdgcn_s_sleep(1);
;     __builtin_amdgcn_fence(__ATOMIC_ACQUIRE, "agent");
;     asm volatile("s_waitcnt vmcnt(0)" ::: "memory");
;   }
;   __syncthreads();
; }
.LBB0_564:
	s_or_b64 exec, exec, s[8:9]
	v_readlane_b32 s3, v254, 12
	s_add_i32 s16, s3, 3
	s_cmp_ge_i32 s16, s79
	s_cbranch_scc1 .LBB0_585
	s_cmp_lg_u32 s2, s78
	s_mov_b64 s[8:9], -1
	s_cbranch_scc0 .LBB0_573
	s_waitcnt vmcnt(0)
	s_waitcnt vmcnt(63) expcnt(7) lgkmcnt(15)
	s_barrier
	s_mov_b64 s[8:9], exec
	v_readlane_b32 s10, v254, 26
	v_readlane_b32 s11, v254, 27
	s_and_b64 s[10:11], s[8:9], s[10:11]
	s_mov_b64 exec, s[10:11]
	s_cbranch_execz .LBB0_572
	s_mov_b64 s[10:11], exec
	buffer_wbl2 sc1
	s_waitcnt vmcnt(0)
	s_waitcnt vmcnt(0)
	v_mbcnt_lo_u32_b32 v0, s10, 0
	s_add_u32 s4, s4, 0x1ee14400
	v_mbcnt_hi_u32_b32 v0, s11, v0
	s_addc_u32 s5, s5, 0
	v_cmp_eq_u32_e32 vcc, 0, v0
	s_and_saveexec_b64 s[12:13], vcc
	s_cbranch_execz .LBB0_569
	s_bcnt1_i32_b64 s3, s[10:11]
	v_mov_b32_e32 v0, s3
	v_readlane_b32 s100, v254, 0
	s_and_b32 s100, s100, 7
	s_lshl_b32 s100, s100, 8
	s_add_u32 s100, s4, s100
	s_addc_u32 s101, s5, 0
	global_atomic_add v1, v0, s[100:101]
.LBB0_569:
	s_or_b64 exec, exec, s[12:13]
	s_mov_b64 exec, 0xff
	v_mbcnt_lo_u32_b32 v3, -1, 0
	v_lshlrev_b32_e32 v3, 8, v3
	global_load_dword v0, v3, s[4:5] sc1
	s_load_dword s3, s[80:81], 0x0
	s_sub_i32 s2, s2, s78
	s_waitcnt lgkmcnt(0)
	s_mul_i32 s2, s3, s2
	s_waitcnt vmcnt(0)
	s_lshr_b32 s2, s2, 3
	v_cmp_gt_u32_e32 vcc, s2, v0
	s_cbranch_vccz .LBB0_571
.LBB0_570:
	s_sleep 1
	global_load_dword v0, v3, s[4:5] sc1
	s_waitcnt vmcnt(0)
	v_cmp_gt_u32_e32 vcc, s2, v0
	s_cbranch_vccnz .LBB0_570

; #define GAS __attribute__((address_space(1)))
; DI void grid_barrier(unsigned* ctr, const unsigned target) {
;   asm volatile("s_waitcnt vmcnt(0)" ::: "memory");
;   __syncthreads();
;   if (threadIdx.x == 0) {
;     __builtin_amdgcn_fence(__ATOMIC_RELEASE, "agent");
;     asm volatile("s_waitcnt vmcnt(0)" ::: "memory");
;     __hip_atomic_fetch_add((GAS unsigned*)ctr, 1u, __ATOMIC_RELAXED, __HIP_MEMORY_SCOPE_AGENT);
;     while (__hip_atomic_load((GAS unsigned*)ctr, __ATOMIC_RELAXED, __HIP_MEMORY_SCOPE_AGENT) < target) __builtin_amdgcn_s_sleep(1);
;     __builtin_amdgcn_fence(__ATOMIC_ACQUIRE, "agent");
;     asm volatile("s_waitcnt vmcnt(0)" ::: "memory");
;   }
;   __syncthreads();
; }
.LBB0_672:
	v_readlane_b32 s2, v254, 12
	s_add_i32 s26, s2, 4
	s_cmp_ge_i32 s26, s79
	s_cbranch_scc1 .LBB0_693
	v_readlane_b32 s14, v254, 46
	s_cmp_lg_u32 s14, s78
	s_mov_b64 s[4:5], -1
	s_cbranch_scc0 .LBB0_681
	s_waitcnt vmcnt(0)
	s_barrier
	s_mov_b64 s[4:5], exec
	v_readlane_b32 s2, v254, 26
	v_readlane_b32 s3, v254, 27
	s_and_b64 s[2:3], s[4:5], s[2:3]
	s_mov_b64 exec, s[2:3]
	s_cbranch_execz .LBB0_680
	v_readlane_b32 s2, v254, 44
	s_add_u32 s6, s2, 0x1ee14400
	s_load_dword s2, s[80:81], 0x0
	s_mov_b64 s[8:9], exec
	buffer_wbl2 sc1
	s_waitcnt vmcnt(0) lgkmcnt(0)
	s_waitcnt vmcnt(0)
	v_mbcnt_lo_u32_b32 v0, s8, 0
	v_readlane_b32 s3, v254, 45
	v_mbcnt_hi_u32_b32 v0, s9, v0
	s_addc_u32 s7, s3, 0
	v_cmp_eq_u32_e32 vcc, 0, v0
	s_and_saveexec_b64 s[10:11], vcc
	s_cbranch_execz .LBB0_677
	s_bcnt1_i32_b64 s3, s[8:9]
	v_mov_b32_e32 v0, s3
	v_readlane_b32 s100, v254, 0
	s_and_b32 s100, s100, 7
	s_lshl_b32 s100, s100, 8
	s_add_u32 s100, s6, s100
	s_addc_u32 s101, s7, 0
	global_atomic_add v1, v0, s[100:101]
.LBB0_677:
	s_or_b64 exec, exec, s[10:11]
	s_mov_b64 exec, 0xff
	v_mbcnt_lo_u32_b32 v3, -1, 0
	v_lshlrev_b32_e32 v3, 8, v3
	global_load_dword v0, v3, s[6:7] sc1
	s_sub_i32 s3, s14, s78
	s_mul_i32 s2, s2, s3
	s_waitcnt vmcnt(0)
	s_lshr_b32 s2, s2, 3
	v_cmp_gt_u32_e32 vcc, s2, v0
	s_cbranch_vccz .LBB0_679

; #define GAS __attribute__((address_space(1)))
; DI void grid_barrier(unsigned* ctr, const unsigned target) {
;   asm volatile("s_waitcnt vmcnt(0)" ::: "memory");
;   __syncthreads();
;   if (threadIdx.x == 0) {
;     __builtin_amdgcn_fence(__ATOMIC_RELEASE, "agent");
;     asm volatile("s_waitcnt vmcnt(0)" ::: "memory");
;     __hip_atomic_fetch_add((GAS unsigned*)ctr, 1u, __ATOMIC_RELAXED, __HIP_MEMORY_SCOPE_AGENT);
;     while (__hip_atomic_load((GAS unsigned*)ctr, __ATOMIC_RELAXED, __HIP_MEMORY_SCOPE_AGENT) < target) __builtin_amdgcn_s_sleep(1);
;     __builtin_amdgcn_fence(__ATOMIC_ACQUIRE, "agent");
;     asm volatile("s_waitcnt vmcnt(0)" ::: "memory");
;   }
;   __syncthreads();
; }
.LBB0_711:
	v_readlane_b32 s2, v254, 12
	s_add_i32 s24, s2, 5
	s_cmp_ge_i32 s24, s79
	v_bfrev_b32_e32 v206, 32
	v_mov_b32_e32 v207, 0xe000000
	s_cbranch_scc1 .LBB0_732
	s_cmp_lg_u32 s26, s78
	s_mov_b64 s[4:5], -1
	s_cbranch_scc0 .LBB0_720
	s_waitcnt vmcnt(0)
	s_barrier
	s_mov_b64 s[4:5], exec
	v_readlane_b32 s2, v254, 26
	v_readlane_b32 s3, v254, 27
	s_and_b64 s[2:3], s[4:5], s[2:3]
	s_mov_b64 exec, s[2:3]
	s_cbranch_execz .LBB0_719
	s_load_dword s2, s[80:81], 0x0
	s_mov_b64 s[8:9], exec
	buffer_wbl2 sc1
	s_waitcnt vmcnt(0) lgkmcnt(0)
	s_waitcnt vmcnt(0)
	v_mbcnt_lo_u32_b32 v0, s8, 0
	s_add_u32 s6, s10, 0x1ee14400
	v_mbcnt_hi_u32_b32 v0, s9, v0
	s_addc_u32 s7, s11, 0
	v_cmp_eq_u32_e32 vcc, 0, v0
	s_and_saveexec_b64 s[10:11], vcc
	s_cbranch_execz .LBB0_716
	s_bcnt1_i32_b64 s3, s[8:9]
	v_mov_b32_e32 v0, s3
	v_readlane_b32 s100, v254, 0
	s_and_b32 s100, s100, 7
	s_lshl_b32 s100, s100, 8
	s_add_u32 s100, s6, s100
	s_addc_u32 s101, s7, 0
	global_atomic_add v1, v0, s[100:101]
.LBB0_716:
	s_or_b64 exec, exec, s[10:11]
	s_mov_b64 exec, 0xff
	v_mbcnt_lo_u32_b32 v3, -1, 0
	v_lshlrev_b32_e32 v3, 8, v3
	global_load_dword v0, v3, s[6:7] sc1
	s_sub_i32 s3, s26, s78
	s_mul_i32 s2, s2, s3
	s_waitcnt vmcnt(0)
	s_lshr_b32 s2, s2, 3
	v_cmp_gt_u32_e32 vcc, s2, v0
	s_cbranch_vccz .LBB0_718

; DI unsigned pk2(float lo, float hi) { f32x2 v = {lo, hi}; bf16x2v b = __builtin_convertvector(v, bf16x2v); return __builtin_bit_cast(unsigned, b); }
; DI float siluf_(float x) { return x * __builtin_amdgcn_rcpf(1.f + __builtin_amdgcn_exp2f(-LOG2E * x)); }
;   DI void operator()(int tok0, int feat0, f32x16 (&acc)[2][2], int r, int hh) const {
;     const int u0 = (feat0 >> 6) * 32;
; #pragma unroll
;     for (int mt = 0; mt < 2; ++mt) {
;       bf16_t* dst = act + (size_t)(tok0 + mt * 32 + r) * DFF + u0 + 16 * hh;
; #pragma unroll
;       for (int gp = 0; gp < 2; ++gp) {
;         u32x4 o;
; #pragma unroll
;         for (int q = 0; q < 4; ++q) { const int i = 8 * gp + 2 * q; o[q] = pk2(siluf_(acc[0][mt][i]) * acc[1][mt][i], siluf_(acc[0][mt][i + 1]) * acc[1][mt][i + 1]); }
;         *(u32x4*)(dst + 8 * gp) = o;
;       }
;     }
;   }
.Lkexit_4:
	v_mov_b32_e32 v0, v192
	v_mov_b64_e32 v[166:167], s[6:7]
	v_ashrrev_i32_e32 v164, 1, v0
	v_and_b32_e32 v164, 0xffffff80, v164
	v_add_u32_e32 v164, s3, v164
	v_ashrrev_i32_e32 v164, 1, v164
	v_and_b32_e32 v165, 0xdf, v0
	v_or_b32_e32 v187, s8, v165
	v_ashrrev_i32_e32 v165, 31, v164
	v_mad_i64_i32 v[188:189], s[12:13], v187, s69, v[166:167]
	v_lshlrev_b64 v[168:169], 1, v[164:165]
	v_lshl_add_u64 v[164:165], v[188:189], 0, v[168:169]
	v_mul_f32_e32 v188, 0xbfb8aa3b, v114
	v_mul_f32_e32 v189, 0xbfb8aa3b, v115
	v_exp_f32_e32 v188, v188
	v_exp_f32_e32 v189, v189
	v_and_b32_e32 v0, 32, v0
	v_lshl_add_u64 v[164:165], v[164:165], 0, v[0:1]
	v_add_f32_e32 v188, 1.0, v188
	v_add_f32_e32 v189, 1.0, v189
	v_rcp_f32_e32 v188, v188
	v_rcp_f32_e32 v189, v189
	s_nop 0
	v_pk_mul_f32 v[114:115], v[114:115], v[188:189]
	s_nop 0
	v_pk_mul_f32 v[98:99], v[98:99], v[114:115]
	s_nop 0
	v_cvt_pk_bf16_f32 v98, v98, v99
	v_mul_f32_e32 v99, 0xbfb8aa3b, v116
	v_exp_f32_e32 v99, v99
	s_nop 0
	v_add_f32_e32 v99, 1.0, v99
	v_rcp_f32_e32 v114, v99
	v_mul_f32_e32 v99, 0xbfb8aa3b, v117
	v_exp_f32_e32 v99, v99
	s_nop 0
	v_add_f32_e32 v99, 1.0, v99
	v_rcp_f32_e32 v115, v99
	s_nop 0
	v_pk_mul_f32 v[114:115], v[116:117], v[114:115]
	s_nop 0
	v_pk_mul_f32 v[100:101], v[100:101], v[114:115]
	s_nop 0
	v_cvt_pk_bf16_f32 v99, v100, v101
	v_mul_f32_e32 v100, 0xbfb8aa3b, v118
	v_mul_f32_e32 v101, 0xbfb8aa3b, v119
	v_exp_f32_e32 v100, v100
	v_exp_f32_e32 v101, v101
	v_add_f32_e32 v100, 1.0, v100
	v_add_f32_e32 v101, 1.0, v101
	v_rcp_f32_e32 v100, v100
	v_rcp_f32_e32 v101, v101
	s_nop 0
	v_pk_mul_f32 v[100:101], v[118:119], v[100:101]
	s_nop 0
	v_pk_mul_f32 v[100:101], v[102:103], v[100:101]
	s_nop 0
	v_cvt_pk_bf16_f32 v100, v100, v101
	v_mul_f32_e32 v101, 0xbfb8aa3b, v120
	v_exp_f32_e32 v101, v101
	s_nop 0
	v_add_f32_e32 v101, 1.0, v101
	v_rcp_f32_e32 v102, v101
	v_mul_f32_e32 v101, 0xbfb8aa3b, v121
	v_exp_f32_e32 v101, v101
	s_nop 0
	v_add_f32_e32 v101, 1.0, v101
	v_rcp_f32_e32 v103, v101
	s_nop 0
	v_pk_mul_f32 v[102:103], v[120:121], v[102:103]
	s_nop 0
	v_pk_mul_f32 v[102:103], v[104:105], v[102:103]
	s_nop 0
	v_cvt_pk_bf16_f32 v101, v102, v103
	global_store_dwordx4 v[164:165], v[98:101], off
	s_nop 1
	v_mul_f32_e32 v98, 0xbfb8aa3b, v122
	v_mul_f32_e32 v99, 0xbfb8aa3b, v123
	v_exp_f32_e32 v98, v98
	v_exp_f32_e32 v99, v99
	v_add_f32_e32 v98, 1.0, v98
	v_add_f32_e32 v99, 1.0, v99
	v_rcp_f32_e32 v98, v98
	v_rcp_f32_e32 v99, v99
	s_nop 0
	v_pk_mul_f32 v[98:99], v[122:123], v[98:99]
	s_nop 0
	v_pk_mul_f32 v[98:99], v[106:107], v[98:99]
	s_nop 0
	v_cvt_pk_bf16_f32 v98, v98, v99
	v_mul_f32_e32 v99, 0xbfb8aa3b, v124
	v_exp_f32_e32 v99, v99
	s_nop 0
	v_add_f32_e32 v99, 1.0, v99
	v_rcp_f32_e32 v100, v99
	v_mul_f32_e32 v99, 0xbfb8aa3b, v125
	v_exp_f32_e32 v99, v99
	s_nop 0
	v_add_f32_e32 v99, 1.0, v99
	v_rcp_f32_e32 v101, v99
	s_nop 0
	v_pk_mul_f32 v[100:101], v[124:125], v[100:101]
	s_nop 0
	v_pk_mul_f32 v[100:101], v[108:109], v[100:101]
	s_nop 0
	v_cvt_pk_bf16_f32 v99, v100, v101
	v_mul_f32_e32 v100, 0xbfb8aa3b, v126
	v_mul_f32_e32 v101, 0xbfb8aa3b, v127
	v_exp_f32_e32 v100, v100
	v_exp_f32_e32 v101, v101
	v_add_f32_e32 v100, 1.0, v100
	v_add_f32_e32 v101, 1.0, v101
	v_rcp_f32_e32 v100, v100
	v_rcp_f32_e32 v101, v101
	s_nop 0
	v_pk_mul_f32 v[100:101], v[126:127], v[100:101]
	s_nop 0
	v_pk_mul_f32 v[100:101], v[110:111], v[100:101]
	s_nop 0
	v_cvt_pk_bf16_f32 v100, v100, v101
	v_mul_f32_e32 v101, 0xbfb8aa3b, v128
	v_exp_f32_e32 v101, v101
	s_nop 0
	v_add_f32_e32 v101, 1.0, v101
	v_rcp_f32_e32 v102, v101
	v_mul_f32_e32 v101, 0xbfb8aa3b, v129
	v_exp_f32_e32 v101, v101
	s_nop 0
	v_add_f32_e32 v101, 1.0, v101
	v_rcp_f32_e32 v103, v101
	s_nop 0
	v_pk_mul_f32 v[102:103], v[128:129], v[102:103]
	s_nop 0
	v_pk_mul_f32 v[102:103], v[112:113], v[102:103]
	s_nop 0
	v_cvt_pk_bf16_f32 v101, v102, v103
	global_store_dwordx4 v[164:165], v[98:101], off offset:16
	s_nop 1
	v_or_b32_e32 v98, 32, v187
	v_mad_i64_i32 v[98:99], s[12:13], v98, s69, v[166:167]
	v_lshl_add_u64 v[98:99], v[98:99], 0, v[168:169]
	v_lshl_add_u64 v[98:99], v[98:99], 0, v[0:1]
	v_mul_f32_e32 v0, 0xbfb8aa3b, v82
	v_exp_f32_e32 v0, v0
	s_nop 0
	v_add_f32_e32 v0, 1.0, v0
	v_rcp_f32_e32 v100, v0
	v_mul_f32_e32 v0, 0xbfb8aa3b, v83
	v_exp_f32_e32 v0, v0
	s_nop 0
	v_add_f32_e32 v0, 1.0, v0
	v_rcp_f32_e32 v101, v0
	v_mul_f32_e32 v0, 0xbfb8aa3b, v84
	v_exp_f32_e32 v0, v0
	v_pk_mul_f32 v[82:83], v[82:83], v[100:101]
	s_nop 0
	v_pk_mul_f32 v[66:67], v[66:67], v[82:83]
	v_add_f32_e32 v0, 1.0, v0
	v_rcp_f32_e32 v82, v0
	v_mul_f32_e32 v0, 0xbfb8aa3b, v85
	v_exp_f32_e32 v0, v0
	v_cvt_pk_bf16_f32 v66, v66, v67
	v_add_f32_e32 v0, 1.0, v0
	v_rcp_f32_e32 v83, v0
	v_mul_f32_e32 v0, 0xbfb8aa3b, v86
	v_exp_f32_e32 v0, v0
	v_pk_mul_f32 v[82:83], v[84:85], v[82:83]
	s_nop 0
	v_pk_mul_f32 v[68:69], v[68:69], v[82:83]
	v_add_f32_e32 v0, 1.0, v0
	v_cvt_pk_bf16_f32 v67, v68, v69
	v_rcp_f32_e32 v68, v0
	v_mul_f32_e32 v0, 0xbfb8aa3b, v87
	v_exp_f32_e32 v0, v0
	s_nop 0
	v_add_f32_e32 v0, 1.0, v0
	v_rcp_f32_e32 v69, v0
	v_mul_f32_e32 v0, 0xbfb8aa3b, v88
	v_exp_f32_e32 v0, v0
	v_pk_mul_f32 v[68:69], v[86:87], v[68:69]
	s_nop 0
	v_pk_mul_f32 v[68:69], v[70:71], v[68:69]
	v_add_f32_e32 v0, 1.0, v0
	v_rcp_f32_e32 v70, v0
	v_mul_f32_e32 v0, 0xbfb8aa3b, v89
	v_exp_f32_e32 v0, v0
	v_cvt_pk_bf16_f32 v68, v68, v69
	v_add_f32_e32 v0, 1.0, v0
	v_rcp_f32_e32 v71, v0
	v_mul_f32_e32 v0, 0xbfb8aa3b, v90
	v_exp_f32_e32 v0, v0
	v_pk_mul_f32 v[70:71], v[88:89], v[70:71]
	s_nop 0
	v_pk_mul_f32 v[70:71], v[72:73], v[70:71]
	v_add_f32_e32 v0, 1.0, v0
	v_cvt_pk_bf16_f32 v69, v70, v71
	global_store_dwordx4 v[98:99], v[66:69], off
	s_nop 1
	v_rcp_f32_e32 v66, v0
; DI unsigned pk2(float lo, float hi) { f32x2 v = {lo, hi}; bf16x2v b = __builtin_convertvector(v, bf16x2v); return __builtin_bit_cast(unsigned, b); }
; DI float siluf_(float x) { return x * __builtin_amdgcn_rcpf(1.f + __builtin_amdgcn_exp2f(-LOG2E * x)); }
;   DI void operator()(int tok0, int feat0, f32x16 (&acc)[2][2], int r, int hh) const {
;     const int u0 = (feat0 >> 6) * 32;
; #pragma unroll
;     for (int mt = 0; mt < 2; ++mt) {
;       bf16_t* dst = act + (size_t)(tok0 + mt * 32 + r) * DFF + u0 + 16 * hh;
; #pragma unroll
;       for (int gp = 0; gp < 2; ++gp) {
;         u32x4 o;
; #pragma unroll
;         for (int q = 0; q < 4; ++q) { const int i = 8 * gp + 2 * q; o[q] = pk2(siluf_(acc[0][mt][i]) * acc[1][mt][i], siluf_(acc[0][mt][i + 1]) * acc[1][mt][i + 1]); }
;         *(u32x4*)(dst + 8 * gp) = o;
;       }
;     }
;   }
	v_mul_f32_e32 v0, 0xbfb8aa3b, v91
	v_exp_f32_e32 v0, v0
	s_nop 0
	v_add_f32_e32 v0, 1.0, v0
	v_rcp_f32_e32 v67, v0
	v_mul_f32_e32 v0, 0xbfb8aa3b, v92
	v_exp_f32_e32 v0, v0
	v_pk_mul_f32 v[66:67], v[90:91], v[66:67]
	s_nop 0
	v_pk_mul_f32 v[66:67], v[74:75], v[66:67]
	v_add_f32_e32 v0, 1.0, v0
	v_rcp_f32_e32 v68, v0
	v_mul_f32_e32 v0, 0xbfb8aa3b, v93
	v_exp_f32_e32 v0, v0
	v_cvt_pk_bf16_f32 v66, v66, v67
	v_add_f32_e32 v0, 1.0, v0
	v_rcp_f32_e32 v69, v0
	v_mul_f32_e32 v0, 0xbfb8aa3b, v94
	v_exp_f32_e32 v0, v0
	v_pk_mul_f32 v[68:69], v[92:93], v[68:69]
	s_nop 0
	v_pk_mul_f32 v[68:69], v[76:77], v[68:69]
	v_add_f32_e32 v0, 1.0, v0
	v_cvt_pk_bf16_f32 v67, v68, v69
	v_rcp_f32_e32 v68, v0
	v_mul_f32_e32 v0, 0xbfb8aa3b, v95
	v_exp_f32_e32 v0, v0
	s_nop 0
	v_add_f32_e32 v0, 1.0, v0
	v_rcp_f32_e32 v69, v0
	v_mul_f32_e32 v0, 0xbfb8aa3b, v96
	v_exp_f32_e32 v0, v0
	v_pk_mul_f32 v[68:69], v[94:95], v[68:69]
	s_nop 0
	v_pk_mul_f32 v[68:69], v[78:79], v[68:69]
	v_add_f32_e32 v0, 1.0, v0
	v_rcp_f32_e32 v70, v0
	v_mul_f32_e32 v0, 0xbfb8aa3b, v97
	v_exp_f32_e32 v0, v0
	v_cvt_pk_bf16_f32 v68, v68, v69
	v_add_f32_e32 v0, 1.0, v0
	v_rcp_f32_e32 v71, v0
	s_nop 0
	v_pk_mul_f32 v[70:71], v[96:97], v[70:71]
	s_nop 0
	v_pk_mul_f32 v[70:71], v[80:81], v[70:71]
	s_nop 0
	v_cvt_pk_bf16_f32 v69, v70, v71
	global_store_dwordx4 v[98:99], v[66:69], off offset:16
	v_mul_f32_e32 v0, 0xbfb8aa3b, v50
	v_exp_f32_e32 v0, v0
	s_nop 0
	v_add_f32_e32 v0, 1.0, v0
	v_rcp_f32_e32 v66, v0
	v_mul_f32_e32 v0, 0xbfb8aa3b, v51
	v_exp_f32_e32 v0, v0
	s_nop 0
	v_add_f32_e32 v0, 1.0, v0
	v_rcp_f32_e32 v67, v0
	v_mul_f32_e32 v0, 0xbfb8aa3b, v52
	v_exp_f32_e32 v0, v0
	v_pk_mul_f32 v[50:51], v[50:51], v[66:67]
	s_nop 0
	v_pk_mul_f32 v[34:35], v[34:35], v[50:51]
	v_add_f32_e32 v0, 1.0, v0
	v_rcp_f32_e32 v50, v0
	v_mul_f32_e32 v0, 0xbfb8aa3b, v53
	v_exp_f32_e32 v0, v0
	v_cvt_pk_bf16_f32 v34, v34, v35
	v_add_f32_e32 v0, 1.0, v0
	v_rcp_f32_e32 v51, v0
	v_mul_f32_e32 v0, 0xbfb8aa3b, v54
	v_exp_f32_e32 v0, v0
	v_pk_mul_f32 v[50:51], v[52:53], v[50:51]
	s_nop 0
	v_pk_mul_f32 v[36:37], v[36:37], v[50:51]
	v_add_f32_e32 v0, 1.0, v0
	v_cvt_pk_bf16_f32 v35, v36, v37
	v_rcp_f32_e32 v36, v0
	v_mul_f32_e32 v0, 0xbfb8aa3b, v55
	v_exp_f32_e32 v0, v0
	s_nop 0
	v_add_f32_e32 v0, 1.0, v0
	v_rcp_f32_e32 v37, v0
	v_mul_f32_e32 v0, 0xbfb8aa3b, v56
	v_exp_f32_e32 v0, v0
	v_pk_mul_f32 v[36:37], v[54:55], v[36:37]
	s_nop 0
	v_pk_mul_f32 v[36:37], v[38:39], v[36:37]
	v_add_f32_e32 v0, 1.0, v0
	v_rcp_f32_e32 v38, v0
	v_mul_f32_e32 v0, 0xbfb8aa3b, v57
	v_exp_f32_e32 v0, v0
	v_cvt_pk_bf16_f32 v36, v36, v37
	v_add_f32_e32 v0, 1.0, v0
	v_rcp_f32_e32 v39, v0
	v_mul_f32_e32 v0, 0xbfb8aa3b, v58
	v_exp_f32_e32 v0, v0
	v_pk_mul_f32 v[38:39], v[56:57], v[38:39]
	s_nop 0
	v_pk_mul_f32 v[38:39], v[40:41], v[38:39]
	v_add_f32_e32 v0, 1.0, v0
	v_cvt_pk_bf16_f32 v37, v38, v39
	global_store_dwordx4 v[164:165], v[34:37], off offset:64
	s_nop 1
	v_rcp_f32_e32 v34, v0
	v_mul_f32_e32 v0, 0xbfb8aa3b, v59
	v_exp_f32_e32 v0, v0
	s_nop 0
	v_add_f32_e32 v0, 1.0, v0
	v_rcp_f32_e32 v35, v0
	v_mul_f32_e32 v0, 0xbfb8aa3b, v60
	v_exp_f32_e32 v0, v0
	v_pk_mul_f32 v[34:35], v[58:59], v[34:35]
	s_nop 0
	v_pk_mul_f32 v[34:35], v[42:43], v[34:35]
	v_add_f32_e32 v0, 1.0, v0
	v_rcp_f32_e32 v36, v0
	v_mul_f32_e32 v0, 0xbfb8aa3b, v61
	v_exp_f32_e32 v0, v0
	v_cvt_pk_bf16_f32 v34, v34, v35
	v_add_f32_e32 v0, 1.0, v0
	v_rcp_f32_e32 v37, v0
	v_mul_f32_e32 v0, 0xbfb8aa3b, v62
	v_exp_f32_e32 v0, v0
	v_pk_mul_f32 v[36:37], v[60:61], v[36:37]
	s_nop 0
	v_pk_mul_f32 v[36:37], v[44:45], v[36:37]
	v_add_f32_e32 v0, 1.0, v0
	v_cvt_pk_bf16_f32 v35, v36, v37
	v_rcp_f32_e32 v36, v0
	v_mul_f32_e32 v0, 0xbfb8aa3b, v63
	v_exp_f32_e32 v0, v0
	s_nop 0
	v_add_f32_e32 v0, 1.0, v0
	v_rcp_f32_e32 v37, v0
	v_mul_f32_e32 v0, 0xbfb8aa3b, v64
	v_exp_f32_e32 v0, v0
	v_pk_mul_f32 v[36:37], v[62:63], v[36:37]
	s_nop 0
	v_pk_mul_f32 v[36:37], v[46:47], v[36:37]
	v_add_f32_e32 v0, 1.0, v0
	v_rcp_f32_e32 v38, v0
	v_mul_f32_e32 v0, 0xbfb8aa3b, v65
	v_exp_f32_e32 v0, v0
	v_cvt_pk_bf16_f32 v36, v36, v37
	v_add_f32_e32 v0, 1.0, v0
	v_rcp_f32_e32 v39, v0
	v_mul_f32_e32 v0, 0xbfb8aa3b, v18
	v_exp_f32_e32 v0, v0
	v_pk_mul_f32 v[38:39], v[64:65], v[38:39]
	s_nop 0
; #define GAS __attribute__((address_space(1)))
; DI unsigned pk2(float lo, float hi) { f32x2 v = {lo, hi}; bf16x2v b = __builtin_convertvector(v, bf16x2v); return __builtin_bit_cast(unsigned, b); }
; DI float siluf_(float x) { return x * __builtin_amdgcn_rcpf(1.f + __builtin_amdgcn_exp2f(-LOG2E * x)); }
;   DI void operator()(int tok0, int feat0, f32x16 (&acc)[2][2], int r, int hh) const {
;     const int u0 = (feat0 >> 6) * 32;
; #pragma unroll
;     for (int mt = 0; mt < 2; ++mt) {
;       bf16_t* dst = act + (size_t)(tok0 + mt * 32 + r) * DFF + u0 + 16 * hh;
; #pragma unroll
;       for (int gp = 0; gp < 2; ++gp) {
;         u32x4 o;
; #pragma unroll
;         for (int q = 0; q < 4; ++q) { const int i = 8 * gp + 2 * q; o[q] = pk2(siluf_(acc[0][mt][i]) * acc[1][mt][i], siluf_(acc[0][mt][i + 1]) * acc[1][mt][i + 1]); }
;         *(u32x4*)(dst + 8 * gp) = o;
;       }
;     }
;   }
; DI void grid_barrier(unsigned* ctr, const unsigned target) {
;   asm volatile("s_waitcnt vmcnt(0)" ::: "memory");
;   __syncthreads();
;   if (threadIdx.x == 0) {
;     __builtin_amdgcn_fence(__ATOMIC_RELEASE, "agent");
;     asm volatile("s_waitcnt vmcnt(0)" ::: "memory");
;     __hip_atomic_fetch_add((GAS unsigned*)ctr, 1u, __ATOMIC_RELAXED, __HIP_MEMORY_SCOPE_AGENT);
;     while (__hip_atomic_load((GAS unsigned*)ctr, __ATOMIC_RELAXED, __HIP_MEMORY_SCOPE_AGENT) < target) __builtin_amdgcn_s_sleep(1);
;     __builtin_amdgcn_fence(__ATOMIC_ACQUIRE, "agent");
;     asm volatile("s_waitcnt vmcnt(0)" ::: "memory");
;   }
;   __syncthreads();
; }
	v_pk_mul_f32 v[38:39], v[48:49], v[38:39]
	v_add_f32_e32 v0, 1.0, v0
	v_cvt_pk_bf16_f32 v37, v38, v39
	global_store_dwordx4 v[164:165], v[34:37], off offset:80
	s_nop 1
	v_rcp_f32_e32 v34, v0
	v_mul_f32_e32 v0, 0xbfb8aa3b, v19
	v_exp_f32_e32 v0, v0
	s_nop 0
	v_add_f32_e32 v0, 1.0, v0
	v_rcp_f32_e32 v35, v0
	v_mul_f32_e32 v0, 0xbfb8aa3b, v20
	v_exp_f32_e32 v0, v0
	v_pk_mul_f32 v[18:19], v[18:19], v[34:35]
	s_nop 0
	v_pk_mul_f32 v[2:3], v[2:3], v[18:19]
	v_add_f32_e32 v0, 1.0, v0
	v_rcp_f32_e32 v18, v0
	v_mul_f32_e32 v0, 0xbfb8aa3b, v21
	v_exp_f32_e32 v0, v0
	v_cvt_pk_bf16_f32 v2, v2, v3
	v_add_f32_e32 v0, 1.0, v0
	v_rcp_f32_e32 v19, v0
	v_mul_f32_e32 v0, 0xbfb8aa3b, v22
	v_exp_f32_e32 v0, v0
	v_pk_mul_f32 v[18:19], v[20:21], v[18:19]
	s_nop 0
	v_pk_mul_f32 v[4:5], v[4:5], v[18:19]
	v_add_f32_e32 v0, 1.0, v0
	v_cvt_pk_bf16_f32 v3, v4, v5
	v_rcp_f32_e32 v4, v0
	v_mul_f32_e32 v0, 0xbfb8aa3b, v23
	v_exp_f32_e32 v0, v0
	s_nop 0
	v_add_f32_e32 v0, 1.0, v0
	v_rcp_f32_e32 v5, v0
	v_mul_f32_e32 v0, 0xbfb8aa3b, v24
	v_exp_f32_e32 v0, v0
	v_pk_mul_f32 v[4:5], v[22:23], v[4:5]
	s_nop 0
	v_pk_mul_f32 v[4:5], v[6:7], v[4:5]
	v_add_f32_e32 v0, 1.0, v0
	v_rcp_f32_e32 v6, v0
	v_mul_f32_e32 v0, 0xbfb8aa3b, v25
	v_exp_f32_e32 v0, v0
	v_cvt_pk_bf16_f32 v4, v4, v5
	v_add_f32_e32 v0, 1.0, v0
	v_rcp_f32_e32 v7, v0
	v_mul_f32_e32 v0, 0xbfb8aa3b, v26
	v_exp_f32_e32 v0, v0
	v_pk_mul_f32 v[6:7], v[24:25], v[6:7]
	s_nop 0
	v_pk_mul_f32 v[6:7], v[8:9], v[6:7]
	v_add_f32_e32 v0, 1.0, v0
	v_cvt_pk_bf16_f32 v5, v6, v7
	global_store_dwordx4 v[98:99], v[2:5], off offset:64
	s_nop 1
	v_rcp_f32_e32 v2, v0
	v_mul_f32_e32 v0, 0xbfb8aa3b, v27
	v_exp_f32_e32 v0, v0
	s_nop 0
	v_add_f32_e32 v0, 1.0, v0
	v_rcp_f32_e32 v3, v0
	v_mul_f32_e32 v0, 0xbfb8aa3b, v28
	v_exp_f32_e32 v0, v0
	v_pk_mul_f32 v[2:3], v[26:27], v[2:3]
	s_nop 0
	v_pk_mul_f32 v[2:3], v[10:11], v[2:3]
	v_add_f32_e32 v0, 1.0, v0
	v_rcp_f32_e32 v4, v0
	v_mul_f32_e32 v0, 0xbfb8aa3b, v29
	v_exp_f32_e32 v0, v0
	v_cvt_pk_bf16_f32 v2, v2, v3
	v_add_f32_e32 v0, 1.0, v0
	v_rcp_f32_e32 v5, v0
	v_mul_f32_e32 v0, 0xbfb8aa3b, v30
	v_exp_f32_e32 v0, v0
	v_pk_mul_f32 v[4:5], v[28:29], v[4:5]
	s_nop 0
	v_pk_mul_f32 v[4:5], v[12:13], v[4:5]
	v_add_f32_e32 v0, 1.0, v0
	v_cvt_pk_bf16_f32 v3, v4, v5
	v_rcp_f32_e32 v4, v0
	v_mul_f32_e32 v0, 0xbfb8aa3b, v31
	v_exp_f32_e32 v0, v0
	s_nop 0
	v_add_f32_e32 v0, 1.0, v0
	v_rcp_f32_e32 v5, v0
	v_mul_f32_e32 v0, 0xbfb8aa3b, v32
	v_exp_f32_e32 v0, v0
	v_pk_mul_f32 v[4:5], v[30:31], v[4:5]
	s_nop 0
	v_pk_mul_f32 v[4:5], v[14:15], v[4:5]
	v_add_f32_e32 v0, 1.0, v0
	v_rcp_f32_e32 v6, v0
	v_mul_f32_e32 v0, 0xbfb8aa3b, v33
	v_exp_f32_e32 v0, v0
	v_cvt_pk_bf16_f32 v4, v4, v5
	v_add_f32_e32 v0, 1.0, v0
	v_rcp_f32_e32 v7, v0
	s_nop 0
	v_pk_mul_f32 v[6:7], v[32:33], v[6:7]
	s_nop 0
	v_pk_mul_f32 v[6:7], v[16:17], v[6:7]
	s_nop 0
	v_cvt_pk_bf16_f32 v5, v6, v7
	global_store_dwordx4 v[98:99], v[2:5], off offset:80
	s_and_b64 vcc, exec, s[4:5]
	s_mov_b32 s16, s9
	s_cbranch_vccz .LBB0_736
	s_add_i32 s25, s24, 1
	s_cmp_ge_i32 s25, s79
	s_cbranch_scc1 .LBB0_762
	s_cmp_lg_u32 s24, s78
	s_mov_b64 s[4:5], -1
	v_mov_b32_e32 v206, v198
	v_mov_b32_e32 v207, v199
	s_cbranch_scc0 .LBB0_750
	s_waitcnt vmcnt(0)
	s_barrier
	s_mov_b64 s[4:5], exec
	v_readlane_b32 s2, v254, 26
	v_readlane_b32 s3, v254, 27
	s_and_b64 s[2:3], s[4:5], s[2:3]
	s_mov_b64 exec, s[2:3]
	s_cbranch_execz .LBB0_749
	s_load_dword s2, s[80:81], 0x0
	s_mov_b64 s[8:9], exec
	buffer_wbl2 sc1
	s_waitcnt vmcnt(0) lgkmcnt(0)
	s_waitcnt vmcnt(0)
	v_mbcnt_lo_u32_b32 v0, s8, 0
	s_add_u32 s6, s10, 0x1ee14400
	v_mbcnt_hi_u32_b32 v0, s9, v0
	s_addc_u32 s7, s11, 0
	v_cmp_eq_u32_e32 vcc, 0, v0
	s_and_saveexec_b64 s[10:11], vcc
	s_cbranch_execz .LBB0_746
	s_bcnt1_i32_b64 s3, s[8:9]
	v_mov_b32_e32 v0, s3
	v_readlane_b32 s100, v254, 0
	s_and_b32 s100, s100, 7
	s_lshl_b32 s100, s100, 8
	s_add_u32 s100, s6, s100
	s_addc_u32 s101, s7, 0
	global_atomic_add v1, v0, s[100:101]
.LBB0_746:
	s_or_b64 exec, exec, s[10:11]
	s_mov_b64 exec, 0xff
	v_mbcnt_lo_u32_b32 v3, -1, 0
	v_lshlrev_b32_e32 v3, 8, v3
	global_load_dword v0, v3, s[6:7] sc1
	s_sub_i32 s3, s24, s78
	s_mul_i32 s2, s2, s3
	s_waitcnt vmcnt(0)
	s_lshr_b32 s2, s2, 3
	v_cmp_gt_u32_e32 vcc, s2, v0
	s_cbranch_vccz .LBB0_748

; #define GAS __attribute__((address_space(1)))
; DI void grid_barrier(unsigned* ctr, const unsigned target) {
;   asm volatile("s_waitcnt vmcnt(0)" ::: "memory");
;   __syncthreads();
;   if (threadIdx.x == 0) {
;     __builtin_amdgcn_fence(__ATOMIC_RELEASE, "agent");
;     asm volatile("s_waitcnt vmcnt(0)" ::: "memory");
;     __hip_atomic_fetch_add((GAS unsigned*)ctr, 1u, __ATOMIC_RELAXED, __HIP_MEMORY_SCOPE_AGENT);
;     while (__hip_atomic_load((GAS unsigned*)ctr, __ATOMIC_RELAXED, __HIP_MEMORY_SCOPE_AGENT) < target) __builtin_amdgcn_s_sleep(1);
;     __builtin_amdgcn_fence(__ATOMIC_ACQUIRE, "agent");
;     asm volatile("s_waitcnt vmcnt(0)" ::: "memory");
;   }
;   __syncthreads();
; }
.LBB0_780:
	s_cmp_lg_u32 s25, s78
	s_mov_b64 s[4:5], -1
	s_cbranch_scc0 .LBB0_788
	s_waitcnt vmcnt(0)
	s_barrier
	s_mov_b64 s[4:5], exec
	v_readlane_b32 s2, v254, 26
	v_readlane_b32 s3, v254, 27
	s_and_b64 s[2:3], s[4:5], s[2:3]
	s_mov_b64 exec, s[2:3]
	s_cbranch_execz .LBB0_787
	s_load_dword s2, s[80:81], 0x0
	s_mov_b64 s[8:9], exec
	buffer_wbl2 sc1
	s_waitcnt vmcnt(0) lgkmcnt(0)
	s_waitcnt vmcnt(0)
	v_mbcnt_lo_u32_b32 v0, s8, 0
	s_add_u32 s6, s14, 0x1ee14400
	v_mbcnt_hi_u32_b32 v0, s9, v0
	s_addc_u32 s7, s15, 0
	v_cmp_eq_u32_e32 vcc, 0, v0
	s_and_saveexec_b64 s[10:11], vcc
	s_cbranch_execz .LBB0_784
	s_bcnt1_i32_b64 s3, s[8:9]
	v_mov_b32_e32 v0, s3
	v_readlane_b32 s100, v254, 0
	s_and_b32 s100, s100, 7
	s_lshl_b32 s100, s100, 8
	s_add_u32 s100, s6, s100
	s_addc_u32 s101, s7, 0
	global_atomic_add v1, v0, s[100:101]
.LBB0_784:
	s_or_b64 exec, exec, s[10:11]
	s_mov_b64 exec, 0xff
	v_mbcnt_lo_u32_b32 v3, -1, 0
	v_lshlrev_b32_e32 v3, 8, v3
	global_load_dword v0, v3, s[6:7] sc1
	s_sub_i32 s3, s25, s78
	s_mul_i32 s2, s2, s3
	s_waitcnt vmcnt(0)
	s_lshr_b32 s2, s2, 3
	v_cmp_gt_u32_e32 vcc, s2, v0
	s_cbranch_vccz .LBB0_786
